# v29 + attention bias tiles: second 383-entry LDS table indexed by rel+127 (-inf below 0, 0 beyond 127): bias and causal mask are one LDS read with immediate offset and one add per score
# baseline (speedup 1.0000x reference)
; #define ALDS __attribute__((address_space(3)))
; __device__ __forceinline__ float attn_head_setup(ALDS unsigned char* lds, const float* relb, int h) {
;     const int tid = threadIdx.x; ALDS float* lut = (ALDS float*)(lds + L_LUT);
;     if (tid < 128) { const int n = tid; int bk; if (n < 16) bk = n; else { const int lg = 16 + (int)(logf((float)n / 16.0f) / logf(8.0f) * 16.0f); bk = lg < 31 ? lg : 31; }
;         lut[tid] = (relb[bk * 8 + h] - relb[31 * 8 + h]) * LOG2E; }
.LBB0_57:
	s_andn2_saveexec_b64 s[6:7], s[6:7]
	s_cbranch_execz .LBB0_59
	s_waitcnt vmcnt(0)
	v_or_b32_e32 v2, s88, v218
	v_ashrrev_i32_e32 v3, 31, v2
	v_lshl_add_u64 v[2:3], v[2:3], 2, s[0:1]
	s_lshl_b32 s8, s88, 2
	v_mov_b32_e32 v1, s8
	global_load_dword v3, v[2:3], off
	s_nop 0
	global_load_dword v2, v1, s[0:1] offset:992
	s_waitcnt vmcnt(0)
	v_sub_f32_e32 v1, v3, v2
	v_mul_f32_e32 v1, 0x3fb8aa3b, v1
	ds_write_b32 v217, v1
	ds_write_b32 v217, v225 offset:4092
	ds_write_b32 v217, v1 offset:4604
	ds_write_b32 v217, v177 offset:5116

.Lattn_b_nodma3:
	ds_read_b128 v[144:147], v115 offset:8192
	s_waitcnt lgkmcnt(4)
	v_mfma_f32_32x32x16_bf16 v[34:49], v[80:83], v[238:241], v[34:49]
	s_waitcnt lgkmcnt(2)
	v_mfma_f32_32x32x16_bf16 v[50:65], v[80:83], v[242:245], v[50:65]
	s_add_i32 s0, s0, -2
	s_cmp_lt_i32 s0, s70
	s_waitcnt lgkmcnt(0)
	v_mfma_f32_32x32x16_bf16 v[96:111], v[172:175], v[140:143], 0
	v_mfma_f32_32x32x16_bf16 v[80:95], v[168:171], v[140:143], 0
	v_mfma_f32_32x32x16_bf16 v[96:111], v[164:167], v[136:139], v[96:111]
	v_mfma_f32_32x32x16_bf16 v[80:95], v[160:163], v[136:139], v[80:95]
	v_mfma_f32_32x32x16_bf16 v[96:111], v[156:159], v[132:135], v[96:111]
	v_mfma_f32_32x32x16_bf16 v[80:95], v[152:155], v[132:135], v[80:95]
	v_mfma_f32_32x32x16_bf16 v[96:111], v[148:151], v[128:131], v[96:111]
	s_nop 1
	v_mfma_f32_32x32x16_bf16 v[80:95], v[144:147], v[128:131], v[80:95]
	s_cbranch_scc1 .LBB0_142
	s_mov_b32 s100, 0x2117c
	v_lshl_add_u32 v249, v209, 2, s100
	ds_read_b32 v112, v249 offset:236
	ds_read_b32 v113, v249 offset:232
	ds_read_b32 v114, v249 offset:228
	ds_read_b32 v115, v249 offset:224
	ds_read_b32 v116, v249 offset:204
	ds_read_b32 v117, v249 offset:200
	ds_read_b32 v118, v249 offset:196
	ds_read_b32 v119, v249 offset:192
	ds_read_b32 v120, v249 offset:172
	ds_read_b32 v121, v249 offset:168
	ds_read_b32 v122, v249 offset:164
	ds_read_b32 v123, v249 offset:160
	ds_read_b32 v124, v249 offset:140
	ds_read_b32 v125, v249 offset:136
	ds_read_b32 v126, v249 offset:132
	ds_read_b32 v127, v249 offset:128
	s_waitcnt lgkmcnt(15)
	v_add_f32_e32 v96, v96, v112
	ds_read_b32 v112, v249 offset:108
	s_waitcnt lgkmcnt(15)
	v_add_f32_e32 v97, v97, v113
	ds_read_b32 v113, v249 offset:104
	s_waitcnt lgkmcnt(15)
	v_add_f32_e32 v98, v98, v114
	ds_read_b32 v114, v249 offset:100
	s_waitcnt lgkmcnt(15)
	v_add_f32_e32 v99, v99, v115
	ds_read_b32 v115, v249 offset:96
	s_waitcnt lgkmcnt(15)
	v_add_f32_e32 v100, v100, v116
	ds_read_b32 v116, v249 offset:76
	s_waitcnt lgkmcnt(15)
	v_add_f32_e32 v101, v101, v117
	ds_read_b32 v117, v249 offset:72
	s_waitcnt lgkmcnt(15)
	v_add_f32_e32 v102, v102, v118
	ds_read_b32 v118, v249 offset:68
	s_waitcnt lgkmcnt(15)
	v_add_f32_e32 v103, v103, v119
	ds_read_b32 v119, v249 offset:64
	s_waitcnt lgkmcnt(15)
	v_add_f32_e32 v104, v104, v120
	ds_read_b32 v120, v249 offset:44
	s_waitcnt lgkmcnt(15)
	v_add_f32_e32 v105, v105, v121
	ds_read_b32 v121, v249 offset:40
	s_waitcnt lgkmcnt(15)
	v_add_f32_e32 v106, v106, v122
	ds_read_b32 v122, v249 offset:36
	s_waitcnt lgkmcnt(15)
	v_add_f32_e32 v107, v107, v123
	ds_read_b32 v123, v249 offset:32
	s_waitcnt lgkmcnt(15)
	v_add_f32_e32 v108, v108, v124
	ds_read_b32 v124, v249 offset:12
	s_waitcnt lgkmcnt(15)
	v_add_f32_e32 v109, v109, v125
	ds_read_b32 v125, v249 offset:8
	s_waitcnt lgkmcnt(15)
	v_add_f32_e32 v110, v110, v126
	ds_read_b32 v126, v249 offset:4
	s_waitcnt lgkmcnt(15)
	v_add_f32_e32 v111, v111, v127
	ds_read_b32 v127, v249 offset:0
	s_waitcnt lgkmcnt(15)
	v_add_f32_e32 v80, v80, v112
	s_waitcnt lgkmcnt(14)
	v_add_f32_e32 v81, v81, v113
	s_waitcnt lgkmcnt(13)
	v_add_f32_e32 v82, v82, v114
	s_waitcnt lgkmcnt(12)
	v_add_f32_e32 v83, v83, v115
	s_waitcnt lgkmcnt(11)
	v_add_f32_e32 v84, v84, v116
	s_waitcnt lgkmcnt(10)
	v_add_f32_e32 v85, v85, v117
	s_waitcnt lgkmcnt(9)
	v_add_f32_e32 v86, v86, v118
	s_waitcnt lgkmcnt(8)
	v_add_f32_e32 v87, v87, v119
	s_waitcnt lgkmcnt(7)
	v_add_f32_e32 v88, v88, v120
	s_waitcnt lgkmcnt(6)
	v_add_f32_e32 v89, v89, v121
	s_waitcnt lgkmcnt(5)
	v_add_f32_e32 v90, v90, v122
	s_waitcnt lgkmcnt(4)
	v_add_f32_e32 v91, v91, v123
	s_waitcnt lgkmcnt(3)
	v_add_f32_e32 v92, v92, v124
	s_waitcnt lgkmcnt(2)
	v_add_f32_e32 v93, v93, v125
	s_waitcnt lgkmcnt(1)
	v_add_f32_e32 v94, v94, v126
	s_waitcnt lgkmcnt(0)
	v_add_f32_e32 v95, v95, v127

.LBB0_154:
.LBB0_155:
	s_add_i32 s0, s93, 0xffff8000
	s_and_b32 s0, s0, 0xc000
	v_add_u32_e32 v112, s0, v198
	v_add_u32_e32 v113, v112, v194
	ds_read_b128 v[172:175], v113
	ds_read_b128 v[168:171], v113 offset:8192
	v_add_u32_e32 v113, v112, v195
	ds_read_b128 v[164:167], v113
	ds_read_b128 v[160:163], v113 offset:8192
	v_add_u32_e32 v113, v112, v196
	v_add_u32_e32 v112, v112, v197
	ds_read_b128 v[156:159], v113
	ds_read_b128 v[152:155], v113 offset:8192
	ds_read_b128 v[148:151], v112
	ds_read_b128 v[144:147], v112 offset:8192
	s_cmp_lt_i32 s70, s99
	s_cbranch_scc1 .LBB0_189
	s_mov_b32 s100, 0x2117c
	v_lshl_add_u32 v249, v203, 2, s100
	ds_read_b32 v112, v249 offset:236
	ds_read_b32 v113, v249 offset:232
	ds_read_b32 v114, v249 offset:228
	ds_read_b32 v115, v249 offset:224
	ds_read_b32 v116, v249 offset:204
	ds_read_b32 v117, v249 offset:200
	ds_read_b32 v118, v249 offset:196
	ds_read_b32 v119, v249 offset:192
	ds_read_b32 v120, v249 offset:172
	ds_read_b32 v121, v249 offset:168
	ds_read_b32 v122, v249 offset:164
	ds_read_b32 v123, v249 offset:160
	ds_read_b32 v124, v249 offset:140
	ds_read_b32 v125, v249 offset:136
	ds_read_b32 v126, v249 offset:132
	ds_read_b32 v127, v249 offset:128
	s_waitcnt lgkmcnt(15)
	v_add_f32_e32 v96, v96, v112
	ds_read_b32 v112, v249 offset:108
	s_waitcnt lgkmcnt(15)
	v_add_f32_e32 v97, v97, v113
	ds_read_b32 v113, v249 offset:104
	s_waitcnt lgkmcnt(15)
	v_add_f32_e32 v98, v98, v114
	ds_read_b32 v114, v249 offset:100
	s_waitcnt lgkmcnt(15)
	v_add_f32_e32 v99, v99, v115
	ds_read_b32 v115, v249 offset:96
	s_waitcnt lgkmcnt(15)
	v_add_f32_e32 v100, v100, v116
	ds_read_b32 v116, v249 offset:76
	s_waitcnt lgkmcnt(15)
	v_add_f32_e32 v101, v101, v117
	ds_read_b32 v117, v249 offset:72
	s_waitcnt lgkmcnt(15)
	v_add_f32_e32 v102, v102, v118
	ds_read_b32 v118, v249 offset:68
	s_waitcnt lgkmcnt(15)
	v_add_f32_e32 v103, v103, v119
	ds_read_b32 v119, v249 offset:64
	s_waitcnt lgkmcnt(15)
	v_add_f32_e32 v104, v104, v120
	ds_read_b32 v120, v249 offset:44
	s_waitcnt lgkmcnt(15)
	v_add_f32_e32 v105, v105, v121
	ds_read_b32 v121, v249 offset:40
	s_waitcnt lgkmcnt(15)
	v_add_f32_e32 v106, v106, v122
	ds_read_b32 v122, v249 offset:36
	s_waitcnt lgkmcnt(15)
	v_add_f32_e32 v107, v107, v123
	ds_read_b32 v123, v249 offset:32
	s_waitcnt lgkmcnt(15)
	v_add_f32_e32 v108, v108, v124
	ds_read_b32 v124, v249 offset:12
	s_waitcnt lgkmcnt(15)
	v_add_f32_e32 v109, v109, v125
	ds_read_b32 v125, v249 offset:8
	s_waitcnt lgkmcnt(15)
	v_add_f32_e32 v110, v110, v126
	ds_read_b32 v126, v249 offset:4
	s_waitcnt lgkmcnt(15)
	v_add_f32_e32 v111, v111, v127
	ds_read_b32 v127, v249 offset:0
	s_waitcnt lgkmcnt(15)
	v_add_f32_e32 v80, v80, v112
	s_waitcnt lgkmcnt(14)
	v_add_f32_e32 v81, v81, v113
	s_waitcnt lgkmcnt(13)
	v_add_f32_e32 v82, v82, v114
	s_waitcnt lgkmcnt(12)
	v_add_f32_e32 v83, v83, v115
	s_waitcnt lgkmcnt(11)
	v_add_f32_e32 v84, v84, v116
	s_waitcnt lgkmcnt(10)
	v_add_f32_e32 v85, v85, v117
	s_waitcnt lgkmcnt(9)
	v_add_f32_e32 v86, v86, v118
	s_waitcnt lgkmcnt(8)
	v_add_f32_e32 v87, v87, v119
	s_waitcnt lgkmcnt(7)
	v_add_f32_e32 v88, v88, v120
	s_waitcnt lgkmcnt(6)
	v_add_f32_e32 v89, v89, v121
	s_waitcnt lgkmcnt(5)
	v_add_f32_e32 v90, v90, v122
	s_waitcnt lgkmcnt(4)
	v_add_f32_e32 v91, v91, v123
	s_waitcnt lgkmcnt(3)
	v_add_f32_e32 v92, v92, v124
	s_waitcnt lgkmcnt(2)
	v_add_f32_e32 v93, v93, v125
	s_waitcnt lgkmcnt(1)
	v_add_f32_e32 v94, v94, v126
	s_waitcnt lgkmcnt(0)
	v_add_f32_e32 v95, v95, v127
